# FoX sample loops: second f32 staging register set, cache tiles loaded two ahead (2 tiles in flight)
# speedup vs baseline: 1.0018x; 1.0018x over previous
; template <int MODE, bool SAMPLE>
; __device__ __forceinline__ void attn_unit(const Params& p, char* lds, int b, int h, int qb) {
;     ...
;     LOADT(jfirst, stg2[NS == 2 ? PAR0 : 0]); if (NS == 2) LOADT(jfirst - 1, stg2[NS == 2 ? (PAR0 ^ 1) : 0]);
.Lfsr_first_f1:
	s_waitcnt vmcnt(0)
	v_mov_b32_e32 v250, v137
	v_mov_b32_e32 v251, v139
	v_mov_b32_e32 v252, v141
	s_lshl_b64 s[4:5], s[54:55], 10
	v_lshl_add_u64 v[66:67], s[4:5], 0, v[168:169]
	v_readlane_b32 s36, v253, 16
	v_lshlrev_b64 v[66:67], 2, v[66:67]
	v_and_b32_e32 v72, 15, v183
	v_lshlrev_b32_e32 v72, 4, v72
	v_sub_u32_e32 v66, v66, v72
	v_readlane_b32 s40, v253, 20
	v_readlane_b32 s41, v253, 21
	v_readlane_b32 s42, v253, 22
	v_readlane_b32 s43, v253, 23
	v_lshl_add_u64 v[68:69], s[40:41], 0, v[66:67]
	v_mov_b32_e32 v165, v1
	v_lshl_add_u64 v[70:71], v[68:69], 0, v[0:1]
	v_lshl_add_u64 v[68:69], v[68:69], 0, v[164:165]
	v_lshl_add_u64 v[66:67], s[42:43], 0, v[66:67]
	global_load_dwordx4 v[234:237], v[70:71], off offset:256 nt
	global_load_dwordx4 v[238:241], v[70:71], off nt
	global_load_dwordx4 v[242:245], v[68:69], off offset:256 nt
	global_load_dwordx4 v[246:249], v[68:69], off nt
	v_lshl_add_u64 v[68:69], v[66:67], 0, v[0:1]
	v_lshl_add_u64 v[66:67], v[66:67], 0, v[164:165]
	global_load_dwordx4 v[210:213], v[68:69], off offset:256 nt
	global_load_dwordx4 v[134:137], v[68:69], off nt
	global_load_dwordx4 v[194:197], v[66:67], off offset:256 nt
	global_load_dwordx4 v[138:141], v[66:67], off nt
	v_cvt_pk_bf16_f32 v66, v102, v103
	v_cvt_pk_bf16_f32 v67, v104, v105
	v_cvt_pk_bf16_f32 v68, v98, v99
	v_cvt_pk_bf16_f32 v69, v100, v101
	ds_write_b128 v133, v[66:69]
	v_cvt_pk_bf16_f32 v66, v110, v111
	v_cvt_pk_bf16_f32 v67, v112, v113
	v_cvt_pk_bf16_f32 v68, v106, v107
	v_cvt_pk_bf16_f32 v69, v108, v109
	ds_write_b128 v198, v[66:69]
	v_cvt_pk_bf16_f32 v66, v122, v123
	v_cvt_pk_bf16_f32 v67, v124, v125
	v_cvt_pk_bf16_f32 v68, v114, v115
	v_cvt_pk_bf16_f32 v69, v116, v117
	s_cmpk_eq_i32 s97, 0xf000
	ds_write_b128 v199, v[66:69] offset:32768
	v_cvt_pk_bf16_f32 v66, v126, v127
	v_cvt_pk_bf16_f32 v67, v128, v129
	v_cvt_pk_bf16_f32 v68, v118, v119
	v_cvt_pk_bf16_f32 v69, v120, v121
	ds_write_b128 v200, v[66:69] offset:32768
	s_branch .Lfsr_join_f1

; template <int MODE, bool SAMPLE>
; __device__ __forceinline__ void attn_unit(const Params& p, char* lds, int b, int h, int qb) {
;     ...
; #pragma unroll
;     ...
;         const int j = 2 * jj + par;
;         if (j > jfirst) continue;
;         const int buf = par;
;         WRITET(buf, stg2[NS == 2 ? par : 0]);
;         if (j >= NS) LOADT(j - NS, stg2[NS == 2 ? par : 0]);
;         __syncthreads();
;         if (wact && j <= jd && var < 2) {
.LBB0_614:
	s_mov_b32 s0, 0xfffe0000
	s_add_i32 s76, s76, -1
	s_addk_i32 s54, 0xff80
	s_addk_i32 s97, 0xfe00
	s_mov_b32 s1, -1
	s_cmpk_eq_i32 s97, 0xee00
	s_cbranch_scc1 .LBB0_630
.LBB0_615:
	v_cndmask_b32_e64 v66, 0, 1, s[74:75]
	s_cmp_lt_u32 s76, 8
	v_lshlrev_b32_e32 v0, 2, v152
	v_lshlrev_b32_e32 v164, 2, v154
	v_cmp_ne_u32_e64 s[0:1], 1, v66
	s_cbranch_scc0 .Lfsr_first_f1
	v_and_b32_e32 v76, 15, v183
	v_bfe_u32 v77, v183, 4, 3
	v_xor_b32_e32 v78, v76, v77
	v_lshrrev_b32_e32 v74, 1, v76
	v_xor_b32_e32 v74, v74, v77
	v_sub_u32_e32 v74, v74, v78
	v_and_b32_e32 v78, 1, v76
	v_lshlrev_b32_e32 v74, 4, v74
	v_lshl_add_u32 v74, v78, 3, v74
	v_lshrrev_b32_e32 v75, 3, v76
	v_lshrrev_b32_e32 v78, 2, v76
	v_sub_u32_e32 v75, v75, v78
	v_lshlrev_b32_e32 v75, 9, v75
	v_and_b32_e32 v78, 7, v76
	v_lshl_add_u32 v75, v78, 3, v75
	v_and_b32_e32 v78, 3, v76
	v_lshlrev_b32_e32 v78, 4, v78
	v_sub_u32_e32 v75, v75, v78
	v_add_u32_e32 v70, v133, v74
	v_add_u32_e32 v71, v198, v74
	v_add_u32_e32 v72, v199, v75
	v_add_u32_e32 v73, v200, v75
	s_waitcnt vmcnt(14)
	v_cvt_pk_bf16_f32 v66, v238, v239
	v_cvt_pk_bf16_f32 v67, v240, v241
	v_cvt_pk_bf16_f32 v68, v234, v235
	v_cvt_pk_bf16_f32 v69, v236, v237
	ds_write_b64 v70, v[66:67] offset:16384
	ds_write_b64 v70, v[68:69] offset:16512
	s_waitcnt vmcnt(12)
	v_cvt_pk_bf16_f32 v66, v246, v247
	v_cvt_pk_bf16_f32 v67, v248, v249
	v_cvt_pk_bf16_f32 v68, v242, v243
	v_cvt_pk_bf16_f32 v69, v244, v245
	ds_write_b64 v71, v[66:67] offset:16384
	ds_write_b64 v71, v[68:69] offset:16512
	s_waitcnt vmcnt(10)
	v_cvt_pk_bf16_f32 v66, v134, v135
	v_cvt_pk_bf16_f32 v67, v136, v137
	v_cvt_pk_bf16_f32 v68, v210, v211
	v_cvt_pk_bf16_f32 v69, v212, v213
	ds_write_b64 v72, v[66:67] offset:49152
	ds_write_b64 v72, v[68:69] offset:50176
	s_waitcnt vmcnt(8)
	v_cvt_pk_bf16_f32 v66, v138, v139
	v_cvt_pk_bf16_f32 v67, v140, v141
	v_cvt_pk_bf16_f32 v68, v194, v195
	v_cvt_pk_bf16_f32 v69, v196, v197
	ds_write_b64 v73, v[66:67] offset:49152
	ds_write_b64 v73, v[68:69] offset:50176
	s_cmpk_eq_i32 s97, 0xf000
	s_cbranch_scc1 .Lns2_dum_f1
	s_lshl_b64 s[4:5], s[54:55], 10
	v_lshl_add_u64 v[66:67], s[4:5], 0, v[168:169]
	v_readlane_b32 s36, v253, 16
	v_lshlrev_b64 v[66:67], 2, v[66:67]
	v_and_b32_e32 v72, 15, v183
	v_lshlrev_b32_e32 v72, 4, v72
	v_sub_u32_e32 v66, v66, v72
	v_readlane_b32 s40, v253, 20
	v_readlane_b32 s41, v253, 21
	v_readlane_b32 s42, v253, 22
	v_readlane_b32 s43, v253, 23
	v_lshl_add_u64 v[68:69], s[40:41], 0, v[66:67]
	v_mov_b32_e32 v165, v1
	v_lshl_add_u64 v[70:71], v[68:69], 0, v[0:1]
	v_lshl_add_u64 v[68:69], v[68:69], 0, v[164:165]
	v_lshl_add_u64 v[66:67], s[42:43], 0, v[66:67]
	global_load_dwordx4 v[234:237], v[70:71], off offset:256 nt
	global_load_dwordx4 v[238:241], v[70:71], off nt
	global_load_dwordx4 v[242:245], v[68:69], off offset:256 nt
	global_load_dwordx4 v[246:249], v[68:69], off nt
	v_lshl_add_u64 v[68:69], v[66:67], 0, v[0:1]
	v_lshl_add_u64 v[66:67], v[66:67], 0, v[164:165]
	global_load_dwordx4 v[210:213], v[68:69], off offset:256 nt
	global_load_dwordx4 v[134:137], v[68:69], off nt
	global_load_dwordx4 v[194:197], v[66:67], off offset:256 nt
	global_load_dwordx4 v[138:141], v[66:67], off nt
	s_branch .Lns2_dj_f1
.Lns2_dum_f1:
	v_readlane_b32 s36, v253, 16
	v_readlane_b32 s40, v253, 20
	v_readlane_b32 s41, v253, 21
	v_readlane_b32 s42, v253, 22
	v_readlane_b32 s43, v253, 23
	global_load_dword v255, v183, s[92:93]
	global_load_dword v255, v183, s[92:93]
	global_load_dword v255, v183, s[92:93]
	global_load_dword v255, v183, s[92:93]
	global_load_dword v255, v183, s[92:93]
	global_load_dword v255, v183, s[92:93]
	global_load_dword v255, v183, s[92:93]
	global_load_dword v255, v183, s[92:93]
.Lns2_dj_f1:
	s_and_b64 vcc, exec, s[0:1]
	v_readlane_b32 s37, v253, 17
	v_readlane_b32 s38, v253, 18
	v_readlane_b32 s39, v253, 19
	v_readlane_b32 s44, v253, 24
	v_readlane_b32 s45, v253, 25
	v_readlane_b32 s46, v253, 26
	v_readlane_b32 s47, v253, 27
	v_readlane_b32 s48, v253, 28
	v_readlane_b32 s49, v253, 29
	v_readlane_b32 s50, v253, 30
	v_readlane_b32 s51, v253, 31
	s_waitcnt lgkmcnt(0)
	s_barrier
	s_cbranch_vccnz .LBB0_622
	v_add_u32_e32 v78, s97, v214
	v_add_u32_e32 v66, 0x11100, v78
	v_add_u32_e32 v67, 0x11180, v78
	v_add_u32_e32 v70, 0x11120, v78
	v_add_u32_e32 v74, 0x11140, v78
	ds_read_b128 v[82:85], v66
	ds_read_b128 v[66:69], v67
	ds_read_b128 v[86:89], v70
	ds_read_b128 v[90:93], v74
	v_add_u32_e32 v70, 0x111a0, v78
	v_add_u32_e32 v74, 0x111c0, v78
	v_add_u32_e32 v79, 0x11160, v78
	v_add_u32_e32 v78, 0x111e0, v78
	v_add_u32_e32 v165, s33, v182
	ds_read_b128 v[94:97], v79
	ds_read_b128 v[78:81], v78
	ds_read_b128 v[202:205], v165
	v_add_u32_e32 v165, 0, v182
	ds_read_b128 v[70:73], v70
	ds_read_b128 v[74:77], v74
	ds_read_b128 v[206:209], v165 offset:16384
	ds_read_b128 v[216:219], v165 offset:24576
	s_waitcnt lgkmcnt(1)
	v_mfma_f32_32x32x16_bf16 v[82:97], v[206:209], v[202:205], v[82:97]
	v_add_u32_e32 v165, s33, v184
	s_waitcnt lgkmcnt(0)
	v_mfma_f32_32x32x16_bf16 v[66:81], v[216:219], v[202:205], v[66:81]
	ds_read_b128 v[202:205], v165
	v_add_u32_e32 v165, 0, v184
	ds_read_b128 v[206:209], v165 offset:16384
	ds_read_b128 v[216:219], v165 offset:24576
	v_add_u32_e32 v165, s33, v185
	s_waitcnt lgkmcnt(1)
	v_mfma_f32_32x32x16_bf16 v[82:97], v[206:209], v[202:205], v[82:97]
	s_waitcnt lgkmcnt(0)
	v_mfma_f32_32x32x16_bf16 v[66:81], v[216:219], v[202:205], v[66:81]
	ds_read_b128 v[202:205], v165
	v_add_u32_e32 v165, 0, v185
	ds_read_b128 v[206:209], v165 offset:16384
	ds_read_b128 v[216:219], v165 offset:24576
	v_add_u32_e32 v165, s33, v186
	s_waitcnt lgkmcnt(1)
	v_mfma_f32_32x32x16_bf16 v[82:97], v[206:209], v[202:205], v[82:97]
	s_waitcnt lgkmcnt(0)
; __device__ __forceinline__ int crow(int r, int hi) { return (r & 3) + 8 * (r >> 2) + 4 * hi; }
; __device__ __forceinline__ void qkt(f32x16& p0, f32x16& p1, const char* Ks, const char* Qs, int r32, int hi) {
; #pragma unroll
;     for (int d0 = 0; d0 < 8; ++d0) { const int cb = (d0 * 16 + hi * 8) * 2;
;         const bf16x8 qv = *reinterpret_cast<const bf16x8*>(Qs + KSWZ(r32, cb));
;         const bf16x8 b0 = *reinterpret_cast<const bf16x8*>(Ks + KSWZ(r32, cb));
;         const bf16x8 b1 = *reinterpret_cast<const bf16x8*>(Ks + KSWZ(32 + r32, cb));
;         p0 = __builtin_amdgcn_mfma_f32_32x32x16_bf16(b0, qv, p0, 0, 0, 0);
;         p1 = __builtin_amdgcn_mfma_f32_32x32x16_bf16(b1, qv, p1, 0, 0, 0); }
; }
; template <int MODE, bool SAMPLE>
; __device__ __forceinline__ void attn_unit(const Params& p, char* lds, int b, int h, int qb) {
;     ...
;                 float pmax = p0[0];
; #pragma unroll
;                 for (int r = 1; r < 16; ++r) pmax = fmaxf(pmax, p0[r]);
; #pragma unroll
;                 for (int r = 0; r < 16; ++r) pmax = fmaxf(pmax, p1[r]);
;                 { auto rr = __builtin_amdgcn_permlane32_swap(__float_as_uint(pmax), __float_as_uint(pmax), false, false); pmax = fmaxf(__uint_as_float(rr[0]), __uint_as_float(rr[1])); }
;                 float alpha = 1.f;
;                 if (!__all(pmax - m_reg <= 8.f)) { const float mn = fmaxf(m_reg, pmax); alpha = __builtin_amdgcn_exp2f(m_reg - mn); m_reg = mn; }
;                 float ps = 0.f;
; #pragma unroll
;                 for (int r = 0; r < 16; ++r) { p0[r] = __builtin_amdgcn_exp2f(p0[r] - m_reg); p1[r] = __builtin_amdgcn_exp2f(p1[r] - m_reg); ps += p0[r] + p1[r]; }
;                 { auto rr = __builtin_amdgcn_permlane32_swap(__float_as_uint(ps), __float_as_uint(ps), false, false); ps = __uint_as_float(rr[0]) + __uint_as_float(rr[1]); }
;                 l_reg = l_reg * alpha + ps;
;                 if (__any(alpha < 1.f)) { if (hi == 0) wsc[r32] = alpha; asm volatile("s_waitcnt lgkmcnt(0)" ::: "memory");
; #pragma unroll
;                     for (int d = 0; d < 4; ++d)
; #pragma unroll
;                         for (int r = 0; r < 16; ++r) o[d][r] *= wsc[crow(r, hi)]; }
	v_mfma_f32_32x32x16_bf16 v[66:81], v[216:219], v[202:205], v[66:81]
	ds_read_b128 v[202:205], v165
	v_add_u32_e32 v165, 0, v186
	ds_read_b128 v[206:209], v165 offset:16384
	ds_read_b128 v[216:219], v165 offset:24576
	v_add_u32_e32 v165, s33, v187
	s_waitcnt lgkmcnt(1)
	v_mfma_f32_32x32x16_bf16 v[82:97], v[206:209], v[202:205], v[82:97]
	s_waitcnt lgkmcnt(0)
	v_mfma_f32_32x32x16_bf16 v[66:81], v[216:219], v[202:205], v[66:81]
	ds_read_b128 v[202:205], v165
	v_add_u32_e32 v165, 0, v187
	ds_read_b128 v[206:209], v165 offset:16384
	ds_read_b128 v[216:219], v165 offset:24576
	v_add_u32_e32 v165, s33, v188
	s_waitcnt lgkmcnt(1)
	v_mfma_f32_32x32x16_bf16 v[82:97], v[206:209], v[202:205], v[82:97]
	s_waitcnt lgkmcnt(0)
	v_mfma_f32_32x32x16_bf16 v[66:81], v[216:219], v[202:205], v[66:81]
	ds_read_b128 v[202:205], v165
	v_add_u32_e32 v165, 0, v188
	ds_read_b128 v[206:209], v165 offset:16384
	ds_read_b128 v[216:219], v165 offset:24576
	v_add_u32_e32 v165, s33, v189
	s_waitcnt lgkmcnt(1)
	v_mfma_f32_32x32x16_bf16 v[82:97], v[206:209], v[202:205], v[82:97]
	s_waitcnt lgkmcnt(0)
	v_mfma_f32_32x32x16_bf16 v[66:81], v[216:219], v[202:205], v[66:81]
	ds_read_b128 v[202:205], v165
	v_add_u32_e32 v165, 0, v189
	ds_read_b128 v[206:209], v165 offset:16384
	ds_read_b128 v[216:219], v165 offset:24576
	v_add_u32_e32 v165, s33, v190
	s_waitcnt lgkmcnt(1)
	v_mfma_f32_32x32x16_bf16 v[82:97], v[206:209], v[202:205], v[82:97]
	s_waitcnt lgkmcnt(0)
	v_mfma_f32_32x32x16_bf16 v[66:81], v[216:219], v[202:205], v[66:81]
	ds_read_b128 v[202:205], v165
	v_add_u32_e32 v165, 0, v190
	ds_read_b128 v[206:209], v165 offset:16384
	ds_read_b128 v[216:219], v165 offset:24576
	s_waitcnt lgkmcnt(1)
	v_mfma_f32_32x32x16_bf16 v[82:97], v[206:209], v[202:205], v[82:97]
	s_waitcnt lgkmcnt(0)
	v_mfma_f32_32x32x16_bf16 v[66:81], v[216:219], v[202:205], v[66:81]
	s_nop 9
	v_max_f32_e32 v165, v83, v83
	v_max_f32_e32 v202, v82, v82
	v_max_f32_e32 v165, v202, v165
	v_max3_f32 v165, v165, v84, v85
	v_max3_f32 v165, v165, v86, v87
	v_max3_f32 v165, v165, v88, v89
	v_max3_f32 v165, v165, v90, v91
	v_max3_f32 v165, v165, v92, v93
	v_max3_f32 v165, v165, v94, v95
	v_max3_f32 v165, v165, v96, v97
	v_max3_f32 v165, v165, v66, v67
	v_max3_f32 v165, v165, v68, v69
	v_max3_f32 v165, v165, v70, v71
	v_max3_f32 v165, v165, v72, v73
	v_max3_f32 v165, v165, v74, v75
	v_max3_f32 v165, v165, v76, v77
	v_max3_f32 v165, v165, v78, v79
	v_max3_f32 v165, v165, v80, v81
	v_mov_b32_e32 v202, v165
	s_nop 1
	v_permlane32_swap_b32_e32 v165, v202
	v_max_f32_e32 v202, v202, v202
	v_max_f32_e32 v165, v165, v165
	v_max_f32_e32 v165, v165, v202
	v_sub_f32_e32 v202, v165, v163
	v_cmp_ge_f32_e32 vcc, s83, v202
	s_cmp_eq_u64 vcc, exec
	v_max_f32_e32 v202, v163, v163
	s_cselect_b64 vcc, -1, 0
	v_max_f32_e32 v165, v202, v165
	v_sub_f32_e32 v202, v163, v165
	v_cndmask_b32_e32 v163, v165, v163, vcc
	v_sub_f32_e32 v82, v82, v163
	v_sub_f32_e32 v66, v66, v163
	v_exp_f32_e32 v165, v82
	v_exp_f32_e32 v82, v66
	v_exp_f32_e32 v203, v202
	v_sub_f32_e32 v67, v67, v163
	v_sub_f32_e32 v68, v68, v163
	v_add_f32_e32 v66, v165, v82
	v_add_f32_e32 v202, 0, v66
	v_sub_f32_e32 v66, v83, v163
	v_exp_f32_e32 v66, v66
	v_exp_f32_e32 v83, v67
	v_sub_f32_e32 v69, v69, v163
	v_sub_f32_e32 v70, v70, v163
	v_exp_f32_e32 v70, v70
	v_add_f32_e32 v67, v66, v83
	v_add_f32_e32 v202, v67, v202
	v_sub_f32_e32 v67, v84, v163
	v_exp_f32_e32 v67, v67
	v_exp_f32_e32 v84, v68
	v_sub_f32_e32 v71, v71, v163
	v_exp_f32_e32 v71, v71
	v_sub_f32_e32 v72, v72, v163
	v_add_f32_e32 v68, v67, v84
	v_add_f32_e32 v202, v68, v202
	v_sub_f32_e32 v68, v85, v163
	v_exp_f32_e32 v68, v68
	v_exp_f32_e32 v85, v69
	v_exp_f32_e32 v72, v72
	v_sub_f32_e32 v73, v73, v163
	v_exp_f32_e32 v73, v73
	v_add_f32_e32 v69, v68, v85
	v_add_f32_e32 v202, v69, v202
	v_sub_f32_e32 v69, v86, v163
	v_exp_f32_e32 v69, v69
	v_sub_f32_e32 v74, v74, v163
	v_exp_f32_e32 v74, v74
	v_sub_f32_e32 v75, v75, v163
	v_add_f32_e32 v86, v69, v70
	v_add_f32_e32 v202, v86, v202
	v_sub_f32_e32 v86, v87, v163
	v_exp_f32_e32 v86, v86
	v_exp_f32_e32 v75, v75
	v_sub_f32_e32 v76, v76, v163
	v_exp_f32_e32 v76, v76
	v_add_f32_e32 v87, v86, v71
	v_add_f32_e32 v202, v87, v202
	v_sub_f32_e32 v87, v88, v163
	v_exp_f32_e32 v87, v87
	v_sub_f32_e32 v77, v77, v163
	v_exp_f32_e32 v77, v77
	v_sub_f32_e32 v78, v78, v163
	v_add_f32_e32 v88, v87, v72
	v_add_f32_e32 v202, v88, v202
	v_sub_f32_e32 v88, v89, v163
	v_exp_f32_e32 v88, v88
	v_exp_f32_e32 v78, v78
	v_sub_f32_e32 v79, v79, v163
	v_exp_f32_e32 v79, v79
	v_add_f32_e32 v89, v88, v73
	v_add_f32_e32 v202, v89, v202
	v_sub_f32_e32 v89, v90, v163
	v_exp_f32_e32 v89, v89
	v_sub_f32_e32 v80, v80, v163
	v_exp_f32_e32 v80, v80
	v_sub_f32_e32 v81, v81, v163
	v_add_f32_e32 v90, v89, v74
	v_add_f32_e32 v202, v90, v202
	v_sub_f32_e32 v90, v91, v163
	v_exp_f32_e32 v90, v90
	v_exp_f32_e32 v81, v81
	v_add_f32_e32 v91, v90, v75
	v_add_f32_e32 v202, v91, v202
	v_sub_f32_e32 v91, v92, v163
	v_exp_f32_e32 v91, v91
	s_nop 0
	v_add_f32_e32 v92, v91, v76
	v_add_f32_e32 v202, v92, v202
	v_sub_f32_e32 v92, v93, v163
	v_exp_f32_e32 v92, v92
	s_nop 0
	v_add_f32_e32 v93, v92, v77
	v_add_f32_e32 v202, v93, v202
	v_sub_f32_e32 v93, v94, v163
	v_exp_f32_e32 v93, v93
	s_nop 0
	v_add_f32_e32 v94, v93, v78
	v_add_f32_e32 v202, v94, v202
	v_sub_f32_e32 v94, v95, v163
	v_exp_f32_e32 v94, v94
	s_nop 0
	v_add_f32_e32 v95, v94, v79
	v_add_f32_e32 v202, v95, v202
	v_sub_f32_e32 v95, v96, v163
	v_exp_f32_e32 v95, v95
	s_nop 0
	v_add_f32_e32 v96, v95, v80
	v_add_f32_e32 v202, v96, v202
	v_sub_f32_e32 v96, v97, v163
	v_exp_f32_e32 v96, v96
	s_nop 0
	v_add_f32_e32 v97, v96, v81
	v_add_f32_e32 v202, v97, v202
	v_cndmask_b32_e64 v97, v203, 1.0, vcc
	v_mov_b32_e32 v203, v202
	s_nop 1
	v_permlane32_swap_b32_e32 v202, v203
	v_cmp_gt_f32_e32 vcc, 1.0, v97
	s_cbranch_vccz .LBB0_621
; __device__ __forceinline__ int crow(int r, int hi) { return (r & 3) + 8 * (r >> 2) + 4 * hi; }
; template <int MODE, bool SAMPLE>
; __device__ __forceinline__ void attn_unit(const Params& p, char* lds, int b, int h, int qb) {
;     ...
;                 if (__any(alpha < 1.f)) { if (hi == 0) wsc[r32] = alpha; asm volatile("s_waitcnt lgkmcnt(0)" ::: "memory");
; #pragma unroll
;                     for (int d = 0; d < 4; ++d)
; #pragma unroll
;                         for (int r = 0; r < 16; ++r) o[d][r] *= wsc[crow(r, hi)]; }
	s_and_saveexec_b64 s[4:5], s[14:15]
	ds_write_b32 v145, v97
	s_or_b64 exec, exec, s[4:5]
	s_waitcnt lgkmcnt(0)
	ds_read_b128 v[204:207], v147 offset:96
	ds_read_b128 v[216:219], v147 offset:64
	ds_read_b128 v[220:223], v147 offset:32
	ds_read_b128 v[224:227], v147
	s_waitcnt lgkmcnt(3)
	v_pk_mul_f32 v[64:65], v[64:65], v[206:207]
	s_waitcnt lgkmcnt(2)
	v_pk_mul_f32 v[60:61], v[60:61], v[218:219]
	s_waitcnt lgkmcnt(1)
	v_pk_mul_f32 v[56:57], v[56:57], v[222:223]
	s_waitcnt lgkmcnt(0)
	v_pk_mul_f32 v[52:53], v[52:53], v[226:227]
	v_pk_mul_f32 v[62:63], v[62:63], v[204:205]
	v_pk_mul_f32 v[58:59], v[58:59], v[216:217]
	v_pk_mul_f32 v[54:55], v[54:55], v[220:221]
	v_pk_mul_f32 v[50:51], v[50:51], v[224:225]
	v_pk_mul_f32 v[48:49], v[48:49], v[206:207]
	v_pk_mul_f32 v[44:45], v[44:45], v[218:219]
	v_pk_mul_f32 v[40:41], v[40:41], v[222:223]
	v_pk_mul_f32 v[36:37], v[36:37], v[226:227]
	v_pk_mul_f32 v[46:47], v[46:47], v[204:205]
	v_pk_mul_f32 v[42:43], v[42:43], v[216:217]
	v_pk_mul_f32 v[38:39], v[38:39], v[220:221]
	v_pk_mul_f32 v[34:35], v[34:35], v[224:225]
	v_pk_mul_f32 v[32:33], v[32:33], v[206:207]
	v_pk_mul_f32 v[28:29], v[28:29], v[218:219]
	v_pk_mul_f32 v[24:25], v[24:25], v[222:223]
	v_pk_mul_f32 v[20:21], v[20:21], v[226:227]
	v_pk_mul_f32 v[30:31], v[30:31], v[204:205]
	v_pk_mul_f32 v[26:27], v[26:27], v[216:217]
	v_pk_mul_f32 v[22:23], v[22:23], v[220:221]
	v_pk_mul_f32 v[18:19], v[18:19], v[224:225]
	v_pk_mul_f32 v[16:17], v[16:17], v[206:207]
	v_pk_mul_f32 v[12:13], v[12:13], v[218:219]
	v_pk_mul_f32 v[8:9], v[8:9], v[222:223]
	v_pk_mul_f32 v[4:5], v[4:5], v[226:227]
	v_pk_mul_f32 v[14:15], v[14:15], v[204:205]
	v_pk_mul_f32 v[10:11], v[10:11], v[216:217]
	v_pk_mul_f32 v[6:7], v[6:7], v[220:221]
	v_pk_mul_f32 v[2:3], v[2:3], v[224:225]

.LBB0_622:
	v_and_b32_e32 v76, 15, v183
	v_bfe_u32 v77, v183, 4, 3
	v_xor_b32_e32 v78, v76, v77
	v_lshrrev_b32_e32 v74, 1, v76
	v_xor_b32_e32 v74, v74, v77
	v_sub_u32_e32 v74, v74, v78
	v_and_b32_e32 v78, 1, v76
	v_lshlrev_b32_e32 v74, 4, v74
	v_lshl_add_u32 v74, v78, 3, v74
	v_lshrrev_b32_e32 v75, 3, v76
	v_lshrrev_b32_e32 v78, 2, v76
	v_sub_u32_e32 v75, v75, v78
	v_lshlrev_b32_e32 v75, 9, v75
	v_and_b32_e32 v78, 7, v76
	v_lshl_add_u32 v75, v78, 3, v75
	v_and_b32_e32 v78, 3, v76
	v_lshlrev_b32_e32 v78, 4, v78
	v_sub_u32_e32 v75, v75, v78
	v_add_u32_e32 v70, v133, v74
	v_add_u32_e32 v71, v198, v74
	v_add_u32_e32 v72, v199, v75
	v_add_u32_e32 v73, v200, v75
	s_waitcnt vmcnt(14)
	v_cvt_pk_bf16_f32 v66, v102, v103
	v_cvt_pk_bf16_f32 v67, v104, v105
	v_cvt_pk_bf16_f32 v68, v98, v99
	v_cvt_pk_bf16_f32 v69, v100, v101
	ds_write_b64 v70, v[66:67]
	ds_write_b64 v70, v[68:69] offset:128
	s_waitcnt vmcnt(12)
	v_cvt_pk_bf16_f32 v66, v110, v111
	v_cvt_pk_bf16_f32 v67, v112, v113
	v_cvt_pk_bf16_f32 v68, v106, v107
	v_cvt_pk_bf16_f32 v69, v108, v109
	ds_write_b64 v71, v[66:67]
	ds_write_b64 v71, v[68:69] offset:128
	s_waitcnt vmcnt(10)
	v_cvt_pk_bf16_f32 v66, v122, v123
	v_cvt_pk_bf16_f32 v67, v124, v125
	v_cvt_pk_bf16_f32 v68, v114, v115
	v_cvt_pk_bf16_f32 v69, v116, v117
	s_cmpk_eq_i32 s97, 0xf000
	ds_write_b64 v72, v[66:67] offset:32768
	ds_write_b64 v72, v[68:69] offset:33792
	s_waitcnt vmcnt(8)
	v_cvt_pk_bf16_f32 v66, v126, v127
	v_cvt_pk_bf16_f32 v67, v128, v129
	v_cvt_pk_bf16_f32 v68, v118, v119
	v_cvt_pk_bf16_f32 v69, v120, v121
	ds_write_b64 v73, v[66:67] offset:32768
	ds_write_b64 v73, v[68:69] offset:33792
.Lfsr_join_f1:
	s_cbranch_scc1 .LBB0_624
	s_mov_b32 s4, 0xfffe0000
	s_mov_b32 s5, -1
	v_lshl_add_u64 v[170:171], v[170:171], 0, s[4:5]
	v_or_b32_e32 v67, s11, v171
	v_or_b32_e32 v66, s3, v170
	v_readlane_b32 s36, v253, 16
	v_lshlrev_b64 v[66:67], 2, v[66:67]
	v_and_b32_e32 v72, 15, v183
	v_lshlrev_b32_e32 v72, 4, v72
	v_sub_u32_e32 v66, v66, v72
	v_readlane_b32 s40, v253, 20
	v_readlane_b32 s41, v253, 21
	v_readlane_b32 s42, v253, 22
	v_readlane_b32 s43, v253, 23
	v_lshl_add_u64 v[68:69], s[40:41], 0, v[66:67]
	v_mov_b32_e32 v165, v1
	v_lshl_add_u64 v[70:71], v[68:69], 0, v[0:1]
	v_lshl_add_u64 v[68:69], v[68:69], 0, v[164:165]
	v_lshl_add_u64 v[66:67], s[42:43], 0, v[66:67]
	global_load_dwordx4 v[98:101], v[70:71], off offset:256 nt
	global_load_dwordx4 v[102:105], v[70:71], off nt
	global_load_dwordx4 v[106:109], v[68:69], off offset:256 nt
	global_load_dwordx4 v[110:113], v[68:69], off nt
	v_lshl_add_u64 v[68:69], v[66:67], 0, v[0:1]
	v_lshl_add_u64 v[66:67], v[66:67], 0, v[164:165]
	global_load_dwordx4 v[114:117], v[68:69], off offset:256 nt
	global_load_dwordx4 v[122:125], v[68:69], off nt
	global_load_dwordx4 v[118:121], v[66:67], off offset:256 nt
	global_load_dwordx4 v[126:129], v[66:67], off nt
	v_readlane_b32 s37, v253, 17
	v_readlane_b32 s38, v253, 18
	v_readlane_b32 s39, v253, 19
	v_readlane_b32 s44, v253, 24
	v_readlane_b32 s45, v253, 25
	v_readlane_b32 s46, v253, 26
	v_readlane_b32 s47, v253, 27
	v_readlane_b32 s48, v253, 28
	v_readlane_b32 s49, v253, 29
	v_readlane_b32 s50, v253, 30
	v_readlane_b32 s51, v253, 31

; __device__ __forceinline__ unsigned cvtpk(float lo, float hi) { unsigned r; asm volatile("v_cvt_pk_bf16_f32 %0, %1, %2" : "=v"(r) : "v"(lo), "v"(hi)); return r; }
; __device__ __forceinline__ int crow(int r, int hi) { return (r & 3) + 8 * (r >> 2) + 4 * hi; }
; template <int MODE, bool SAMPLE>
; __device__ __forceinline__ void attn_unit(const Params& p, char* lds, int b, int h, int qb) {
;     ...
;     if (wact && var < 1) {
;         bf16_t* MIX = (bf16_t*)(p.ws + (var == 0 ? WS_MIX : WS_ACT));
;         const size_t rbase = SAMPLE ? (size_t)(MP + b * TS) : (size_t)(b * SEQ + qb * 256 + wid * 32);
;         constexpr int NIT = SAMPLE ? 4 : 8; const int er = lane >> 4, ec = (lane & 15) * 8;
;         float rli[16];
;         if (MODE == 0) { if (hi == 0) wsc[32 + r32] = l_reg; asm volatile("s_waitcnt lgkmcnt(0)" ::: "memory");
; #pragma unroll
;             for (int r = 0; r < 16; ++r) rli[r] = __builtin_amdgcn_rcpf(wsc[32 + crow(r, hi)]); }
; #pragma unroll
;         for (int r = 0; r < 16; ++r) { const int orow = crow(r, hi);
;             if (!SAMPLE || orow < TS) {
; #pragma unroll
;                 for (int d0 = 0; d0 < 4; ++d0) { float ov = o[d0][r]; if (MODE == 0) ov *= rli[r];
;                     const unsigned pk = cvtpk(ov, 0.f); *(bf16_t*)(Qs + orow * 256 + (d0 * 32 + r32) * 2) = (bf16_t)(pk & 0xffffu); } } }
.LBB0_630:
	s_waitcnt vmcnt(0)
	v_mov_b32_e32 v137, v250
	v_mov_b32_e32 v139, v251
	v_mov_b32_e32 v141, v252
	v_lshlrev_b32_e32 v134, 5, v183
	v_lshlrev_b32_e32 v135, 8, v131
	v_or_b32_e32 v136, 4, v130
	v_or_b32_e32 v138, 8, v130
	v_or_b32_e32 v140, 12, v130
	v_lshlrev_b32_e32 v194, 8, v130
	v_lshlrev_b32_e32 v195, 8, v136
	v_lshlrev_b32_e32 v196, 8, v138
	v_lshlrev_b32_e32 v197, 8, v140
	v_and_b32_e32 v210, 15, v183
	v_lshlrev_b32_e32 v211, 4, v183
	v_lshrrev_b32_e32 v212, 4, v183
	v_add_u32_e32 v213, 32, v212
	s_andn2_b64 vcc, exec, s[72:73]
	s_mov_b64 s[0:1], -1
	s_cbranch_vccnz .LBB0_632
	s_mov_b32 s3, s55
	s_mov_b64 s[0:1], 0

; template <int MODE, bool SAMPLE>
; __device__ __forceinline__ void attn_unit(const Params& p, char* lds, int b, int h, int qb) {
;     ...
;         WRITET(buf, stg2[NS == 2 ? par : 0]);
;         if (j >= NS) LOADT(j - NS, stg2[NS == 2 ? par : 0]);
.Lfsr_first_f2:
	s_waitcnt vmcnt(0)
	v_mov_b32_e32 v250, v141
	v_mov_b32_e32 v251, v143
	v_mov_b32_e32 v252, v130
	s_lshl_b64 s[2:3], s[52:53], 10
	v_lshl_add_u64 v[66:67], s[2:3], 0, v[166:167]
	v_readlane_b32 s36, v253, 16
	v_lshlrev_b64 v[66:67], 2, v[66:67]
	v_and_b32_e32 v72, 15, v183
	v_lshlrev_b32_e32 v72, 4, v72
	v_sub_u32_e32 v66, v66, v72
	v_readlane_b32 s40, v253, 20
	v_readlane_b32 s41, v253, 21
	v_readlane_b32 s42, v253, 22
	v_readlane_b32 s43, v253, 23
	v_lshl_add_u64 v[68:69], s[40:41], 0, v[66:67]
	v_mov_b32_e32 v163, v1
	v_lshl_add_u64 v[70:71], v[68:69], 0, v[0:1]
	v_lshl_add_u64 v[68:69], v[68:69], 0, v[162:163]
	v_lshl_add_u64 v[66:67], s[42:43], 0, v[66:67]
	global_load_dwordx4 v[230:233], v[70:71], off offset:256 nt
	global_load_dwordx4 v[234:237], v[70:71], off nt
	global_load_dwordx4 v[238:241], v[68:69], off offset:256 nt
	global_load_dwordx4 v[242:245], v[68:69], off nt
	v_lshl_add_u64 v[68:69], v[66:67], 0, v[0:1]
	v_lshl_add_u64 v[66:67], v[66:67], 0, v[162:163]
	global_load_dwordx4 v[246:249], v[68:69], off offset:256 nt
	global_load_dwordx4 v[130:133], v[68:69], off nt
	global_load_dwordx4 v[192:195], v[66:67], off offset:256 nt
	global_load_dwordx4 v[140:143], v[66:67], off nt
	v_cvt_pk_bf16_f32 v66, v102, v103
	v_cvt_pk_bf16_f32 v67, v104, v105
	v_cvt_pk_bf16_f32 v68, v98, v99
	v_cvt_pk_bf16_f32 v69, v100, v101
	ds_write_b128 v198, v[66:69]
	v_cvt_pk_bf16_f32 v66, v110, v111
	v_cvt_pk_bf16_f32 v67, v112, v113
	v_cvt_pk_bf16_f32 v68, v106, v107
	v_cvt_pk_bf16_f32 v69, v108, v109
	ds_write_b128 v199, v[66:69]
	v_cvt_pk_bf16_f32 v66, v122, v123
	v_cvt_pk_bf16_f32 v67, v124, v125
	v_cvt_pk_bf16_f32 v68, v114, v115
	v_cvt_pk_bf16_f32 v69, v116, v117
	s_cmpk_eq_i32 s96, 0xf000
	ds_write_b128 v200, v[66:69] offset:32768
	v_cvt_pk_bf16_f32 v66, v126, v127
	v_cvt_pk_bf16_f32 v67, v128, v129
	v_cvt_pk_bf16_f32 v68, v118, v119
	v_cvt_pk_bf16_f32 v69, v120, v121
	ds_write_b128 v201, v[66:69] offset:32768
	s_branch .Lfsr_join_f2

; template <int MODE, bool SAMPLE>
; __device__ __forceinline__ void attn_unit(const Params& p, char* lds, int b, int h, int qb) {
;     ...
; #pragma unroll
;     ...
;         const int j = 2 * jj + par;
;         if (j > jfirst) continue;
;         const int buf = par;
;         WRITET(buf, stg2[NS == 2 ? par : 0]);
;         if (j >= NS) LOADT(j - NS, stg2[NS == 2 ? par : 0]);
.LBB0_843:
	s_mov_b32 s0, 0xfffe0000
	s_add_i32 s55, s55, -1
	s_addk_i32 s52, 0xff80
	s_addk_i32 s96, 0xfe00
	s_mov_b32 s1, -1
	s_cmpk_eq_i32 s96, 0xee00
	s_cbranch_scc1 .LBB0_859
.LBB0_844:
	v_cndmask_b32_e64 v66, 0, 1, s[74:75]
	s_cmp_lt_u32 s55, 8
	v_lshlrev_b32_e32 v0, 2, v150
	v_lshlrev_b32_e32 v162, 2, v152
	v_cmp_ne_u32_e64 s[0:1], 1, v66
	s_cbranch_scc0 .Lfsr_first_f2
	v_and_b32_e32 v76, 15, v183
	v_bfe_u32 v77, v183, 4, 3
	v_xor_b32_e32 v78, v76, v77
	v_lshrrev_b32_e32 v74, 1, v76
	v_xor_b32_e32 v74, v74, v77
	v_sub_u32_e32 v74, v74, v78
	v_and_b32_e32 v78, 1, v76
	v_lshlrev_b32_e32 v74, 4, v74
	v_lshl_add_u32 v74, v78, 3, v74
	v_lshrrev_b32_e32 v75, 3, v76
	v_lshrrev_b32_e32 v78, 2, v76
	v_sub_u32_e32 v75, v75, v78
	v_lshlrev_b32_e32 v75, 9, v75
	v_and_b32_e32 v78, 7, v76
	v_lshl_add_u32 v75, v78, 3, v75
	v_and_b32_e32 v78, 3, v76
	v_lshlrev_b32_e32 v78, 4, v78
	v_sub_u32_e32 v75, v75, v78
	v_add_u32_e32 v70, v198, v74
	v_add_u32_e32 v71, v199, v74
	v_add_u32_e32 v72, v200, v75
	v_add_u32_e32 v73, v201, v75
	s_waitcnt vmcnt(14)
	v_cvt_pk_bf16_f32 v66, v234, v235
	v_cvt_pk_bf16_f32 v67, v236, v237
	v_cvt_pk_bf16_f32 v68, v230, v231
	v_cvt_pk_bf16_f32 v69, v232, v233
	ds_write_b64 v70, v[66:67] offset:16384
	ds_write_b64 v70, v[68:69] offset:16512
	s_waitcnt vmcnt(12)
	v_cvt_pk_bf16_f32 v66, v242, v243
	v_cvt_pk_bf16_f32 v67, v244, v245
	v_cvt_pk_bf16_f32 v68, v238, v239
	v_cvt_pk_bf16_f32 v69, v240, v241
	ds_write_b64 v71, v[66:67] offset:16384
	ds_write_b64 v71, v[68:69] offset:16512
	s_waitcnt vmcnt(10)
	v_cvt_pk_bf16_f32 v66, v130, v131
	v_cvt_pk_bf16_f32 v67, v132, v133
	v_cvt_pk_bf16_f32 v68, v246, v247
	v_cvt_pk_bf16_f32 v69, v248, v249
	ds_write_b64 v72, v[66:67] offset:49152
	ds_write_b64 v72, v[68:69] offset:50176
	s_waitcnt vmcnt(8)
	v_cvt_pk_bf16_f32 v66, v140, v141
	v_cvt_pk_bf16_f32 v67, v142, v143
	v_cvt_pk_bf16_f32 v68, v192, v193
	v_cvt_pk_bf16_f32 v69, v194, v195
	ds_write_b64 v73, v[66:67] offset:49152
	ds_write_b64 v73, v[68:69] offset:50176
	s_cmpk_eq_i32 s96, 0xf000
	s_cbranch_scc1 .Lns2_dum_f2
	s_lshl_b64 s[2:3], s[52:53], 10
	v_lshl_add_u64 v[66:67], s[2:3], 0, v[166:167]
	v_readlane_b32 s36, v253, 16
	v_lshlrev_b64 v[66:67], 2, v[66:67]
	v_and_b32_e32 v72, 15, v183
	v_lshlrev_b32_e32 v72, 4, v72
	v_sub_u32_e32 v66, v66, v72
	v_readlane_b32 s40, v253, 20
	v_readlane_b32 s41, v253, 21
	v_readlane_b32 s42, v253, 22
	v_readlane_b32 s43, v253, 23
	v_lshl_add_u64 v[68:69], s[40:41], 0, v[66:67]
	v_mov_b32_e32 v163, v1
	v_lshl_add_u64 v[70:71], v[68:69], 0, v[0:1]
	v_lshl_add_u64 v[68:69], v[68:69], 0, v[162:163]
	v_lshl_add_u64 v[66:67], s[42:43], 0, v[66:67]
	global_load_dwordx4 v[230:233], v[70:71], off offset:256 nt
	global_load_dwordx4 v[234:237], v[70:71], off nt
	global_load_dwordx4 v[238:241], v[68:69], off offset:256 nt
	global_load_dwordx4 v[242:245], v[68:69], off nt
	v_lshl_add_u64 v[68:69], v[66:67], 0, v[0:1]
	v_lshl_add_u64 v[66:67], v[66:67], 0, v[162:163]
	global_load_dwordx4 v[246:249], v[68:69], off offset:256 nt
	global_load_dwordx4 v[130:133], v[68:69], off nt
	global_load_dwordx4 v[192:195], v[66:67], off offset:256 nt
	global_load_dwordx4 v[140:143], v[66:67], off nt
	s_branch .Lns2_dj_f2

; __device__ __forceinline__ void qkt(f32x16& p0, f32x16& p1, const char* Ks, const char* Qs, int r32, int hi) {
; #pragma unroll
;     for (int d0 = 0; d0 < 8; ++d0) { const int cb = (d0 * 16 + hi * 8) * 2;
;         const bf16x8 qv = *reinterpret_cast<const bf16x8*>(Qs + KSWZ(r32, cb));
;         const bf16x8 b0 = *reinterpret_cast<const bf16x8*>(Ks + KSWZ(r32, cb));
;         const bf16x8 b1 = *reinterpret_cast<const bf16x8*>(Ks + KSWZ(32 + r32, cb));
;         p0 = __builtin_amdgcn_mfma_f32_32x32x16_bf16(b0, qv, p0, 0, 0, 0);
;         p1 = __builtin_amdgcn_mfma_f32_32x32x16_bf16(b1, qv, p1, 0, 0, 0); }
; }
; template <int MODE, bool SAMPLE>
; __device__ __forceinline__ void attn_unit(const Params& p, char* lds, int b, int h, int qb) {
;     ...
;             if (MODE == 0) {
;                 const float* bt = biasL + j * 64 + 4 * hi;
; #pragma unroll
;                 for (int g = 0; g < 4; ++g) { const f32x4 a = *(const f32x4*)(bt + 8 * g), c = *(const f32x4*)(bt + 32 + 8 * g);
; #pragma unroll
;                     for (int i = 0; i < 4; ++i) { p0[4 * g + i] = a[i]; p1[4 * g + i] = c[i]; } }
;                 qkt(p0, p1, Kt, Qs, r32, hi);
.Lns2_dj_f2:
	s_and_b64 vcc, exec, s[0:1]
	v_readlane_b32 s37, v253, 17
	v_readlane_b32 s38, v253, 18
	v_readlane_b32 s39, v253, 19
	v_readlane_b32 s44, v253, 24
	v_readlane_b32 s45, v253, 25
	v_readlane_b32 s46, v253, 26
	v_readlane_b32 s47, v253, 27
	v_readlane_b32 s48, v253, 28
	v_readlane_b32 s49, v253, 29
	v_readlane_b32 s50, v253, 30
	v_readlane_b32 s51, v253, 31
	s_waitcnt lgkmcnt(0)
	s_barrier
	s_cbranch_vccnz .LBB0_851
	v_add_u32_e32 v78, s96, v135
	v_add_u32_e32 v66, 0x11100, v78
	v_add_u32_e32 v67, 0x11180, v78
	v_add_u32_e32 v70, 0x11120, v78
	v_add_u32_e32 v74, 0x11140, v78
	ds_read_b128 v[82:85], v66
	ds_read_b128 v[66:69], v67
	ds_read_b128 v[86:89], v70
	ds_read_b128 v[90:93], v74
	v_add_u32_e32 v70, 0x111a0, v78
	v_add_u32_e32 v74, 0x111c0, v78
	v_add_u32_e32 v79, 0x11160, v78
	v_add_u32_e32 v78, 0x111e0, v78
	v_add_u32_e32 v163, s33, v181
	ds_read_b128 v[94:97], v79
	ds_read_b128 v[78:81], v78
	ds_read_b128 v[204:207], v163
	v_add_u32_e32 v163, 0, v181
	ds_read_b128 v[70:73], v70
	ds_read_b128 v[74:77], v74
	ds_read_b128 v[212:215], v163 offset:16384
	ds_read_b128 v[216:219], v163 offset:24576
	s_waitcnt lgkmcnt(1)
	v_mfma_f32_32x32x16_bf16 v[82:97], v[212:215], v[204:207], v[82:97]
	v_add_u32_e32 v163, s33, v182
	s_waitcnt lgkmcnt(0)
	v_mfma_f32_32x32x16_bf16 v[66:81], v[216:219], v[204:207], v[66:81]
	ds_read_b128 v[204:207], v163
	v_add_u32_e32 v163, 0, v182
	ds_read_b128 v[212:215], v163 offset:16384
	ds_read_b128 v[216:219], v163 offset:24576
	v_add_u32_e32 v163, s33, v184
	s_waitcnt lgkmcnt(1)
	v_mfma_f32_32x32x16_bf16 v[82:97], v[212:215], v[204:207], v[82:97]
	s_waitcnt lgkmcnt(0)
	v_mfma_f32_32x32x16_bf16 v[66:81], v[216:219], v[204:207], v[66:81]
	ds_read_b128 v[204:207], v163
	v_add_u32_e32 v163, 0, v184
	ds_read_b128 v[212:215], v163 offset:16384
	ds_read_b128 v[216:219], v163 offset:24576
	v_add_u32_e32 v163, s33, v185
	s_waitcnt lgkmcnt(1)
	v_mfma_f32_32x32x16_bf16 v[82:97], v[212:215], v[204:207], v[82:97]
	s_waitcnt lgkmcnt(0)
	v_mfma_f32_32x32x16_bf16 v[66:81], v[216:219], v[204:207], v[66:81]
	ds_read_b128 v[204:207], v163
	v_add_u32_e32 v163, 0, v185
	ds_read_b128 v[212:215], v163 offset:16384
	ds_read_b128 v[216:219], v163 offset:24576
	v_add_u32_e32 v163, s33, v186
	s_waitcnt lgkmcnt(1)
	v_mfma_f32_32x32x16_bf16 v[82:97], v[212:215], v[204:207], v[82:97]
	s_waitcnt lgkmcnt(0)
	v_mfma_f32_32x32x16_bf16 v[66:81], v[216:219], v[204:207], v[66:81]
	ds_read_b128 v[204:207], v163
	v_add_u32_e32 v163, 0, v186
	ds_read_b128 v[212:215], v163 offset:16384
	ds_read_b128 v[216:219], v163 offset:24576
	v_add_u32_e32 v163, s33, v187
	s_waitcnt lgkmcnt(1)
	v_mfma_f32_32x32x16_bf16 v[82:97], v[212:215], v[204:207], v[82:97]
	s_waitcnt lgkmcnt(0)
	v_mfma_f32_32x32x16_bf16 v[66:81], v[216:219], v[204:207], v[66:81]
	ds_read_b128 v[204:207], v163
	v_add_u32_e32 v163, 0, v187
	ds_read_b128 v[212:215], v163 offset:16384
	ds_read_b128 v[216:219], v163 offset:24576
	v_add_u32_e32 v163, s33, v188
	s_waitcnt lgkmcnt(1)
	v_mfma_f32_32x32x16_bf16 v[82:97], v[212:215], v[204:207], v[82:97]
	s_waitcnt lgkmcnt(0)
	v_mfma_f32_32x32x16_bf16 v[66:81], v[216:219], v[204:207], v[66:81]
	ds_read_b128 v[204:207], v163
	v_add_u32_e32 v163, 0, v188
	ds_read_b128 v[212:215], v163 offset:16384
	ds_read_b128 v[216:219], v163 offset:24576
	v_add_u32_e32 v163, s33, v189
	s_waitcnt lgkmcnt(1)
	v_mfma_f32_32x32x16_bf16 v[82:97], v[212:215], v[204:207], v[82:97]
	s_waitcnt lgkmcnt(0)
	v_mfma_f32_32x32x16_bf16 v[66:81], v[216:219], v[204:207], v[66:81]
	ds_read_b128 v[204:207], v163
	v_add_u32_e32 v163, 0, v189
	ds_read_b128 v[212:215], v163 offset:16384
	ds_read_b128 v[216:219], v163 offset:24576
	s_waitcnt lgkmcnt(1)
	v_mfma_f32_32x32x16_bf16 v[82:97], v[212:215], v[204:207], v[82:97]
	s_waitcnt lgkmcnt(0)
; __device__ __forceinline__ int crow(int r, int hi) { return (r & 3) + 8 * (r >> 2) + 4 * hi; }
; template <int MODE, bool SAMPLE>
; __device__ __forceinline__ void attn_unit(const Params& p, char* lds, int b, int h, int qb) {
;     ...
;                 float pmax = p0[0];
; #pragma unroll
;                 for (int r = 1; r < 16; ++r) pmax = fmaxf(pmax, p0[r]);
; #pragma unroll
;                 for (int r = 0; r < 16; ++r) pmax = fmaxf(pmax, p1[r]);
;                 { auto rr = __builtin_amdgcn_permlane32_swap(__float_as_uint(pmax), __float_as_uint(pmax), false, false); pmax = fmaxf(__uint_as_float(rr[0]), __uint_as_float(rr[1])); }
;                 float alpha = 1.f;
;                 if (!__all(pmax - m_reg <= 8.f)) { const float mn = fmaxf(m_reg, pmax); alpha = __builtin_amdgcn_exp2f(m_reg - mn); m_reg = mn; }
;                 float ps = 0.f;
; #pragma unroll
;                 for (int r = 0; r < 16; ++r) { p0[r] = __builtin_amdgcn_exp2f(p0[r] - m_reg); p1[r] = __builtin_amdgcn_exp2f(p1[r] - m_reg); ps += p0[r] + p1[r]; }
;                 { auto rr = __builtin_amdgcn_permlane32_swap(__float_as_uint(ps), __float_as_uint(ps), false, false); ps = __uint_as_float(rr[0]) + __uint_as_float(rr[1]); }
;                 l_reg = l_reg * alpha + ps;
;                 if (__any(alpha < 1.f)) { if (hi == 0) wsc[r32] = alpha; asm volatile("s_waitcnt lgkmcnt(0)" ::: "memory");
; #pragma unroll
;                     for (int d = 0; d < 4; ++d)
; #pragma unroll
;                         for (int r = 0; r < 16; ++r) o[d][r] *= wsc[crow(r, hi)]; }
	v_mfma_f32_32x32x16_bf16 v[66:81], v[216:219], v[204:207], v[66:81]
	s_nop 9
	v_max_f32_e32 v163, v83, v83
	v_max_f32_e32 v203, v82, v82
	v_max_f32_e32 v163, v203, v163
	v_max3_f32 v163, v163, v84, v85
	v_max3_f32 v163, v163, v86, v87
	v_max3_f32 v163, v163, v88, v89
	v_max3_f32 v163, v163, v90, v91
	v_max3_f32 v163, v163, v92, v93
	v_max3_f32 v163, v163, v94, v95
	v_max3_f32 v163, v163, v96, v97
	v_max3_f32 v163, v163, v66, v67
	v_max3_f32 v163, v163, v68, v69
	v_max3_f32 v163, v163, v70, v71
	v_max3_f32 v163, v163, v72, v73
	v_max3_f32 v163, v163, v74, v75
	v_max3_f32 v163, v163, v76, v77
	v_max3_f32 v163, v163, v78, v79
	v_max3_f32 v163, v163, v80, v81
	v_mov_b32_e32 v203, v163
	s_nop 1
	v_permlane32_swap_b32_e32 v163, v203
	v_max_f32_e32 v203, v203, v203
	v_max_f32_e32 v163, v163, v163
	v_max_f32_e32 v163, v163, v203
	v_sub_f32_e32 v203, v163, v161
	v_cmp_ge_f32_e32 vcc, s82, v203
	s_cmp_eq_u64 vcc, exec
	v_max_f32_e32 v203, v161, v161
	s_cselect_b64 vcc, -1, 0
	v_max_f32_e32 v163, v203, v163
	v_sub_f32_e32 v203, v161, v163
	v_cndmask_b32_e32 v161, v163, v161, vcc
	v_sub_f32_e32 v82, v82, v161
	v_sub_f32_e32 v66, v66, v161
	v_exp_f32_e32 v163, v82
	v_exp_f32_e32 v82, v66
	v_exp_f32_e32 v204, v203
	v_sub_f32_e32 v67, v67, v161
	v_sub_f32_e32 v68, v68, v161
	v_add_f32_e32 v66, v163, v82
	v_add_f32_e32 v203, 0, v66
	v_sub_f32_e32 v66, v83, v161
	v_exp_f32_e32 v66, v66
	v_exp_f32_e32 v83, v67
	v_sub_f32_e32 v69, v69, v161
	v_sub_f32_e32 v70, v70, v161
	v_exp_f32_e32 v70, v70
	v_add_f32_e32 v67, v66, v83
	v_add_f32_e32 v203, v67, v203
	v_sub_f32_e32 v67, v84, v161
	v_exp_f32_e32 v67, v67
	v_exp_f32_e32 v84, v68
	v_sub_f32_e32 v71, v71, v161
	v_exp_f32_e32 v71, v71
	v_sub_f32_e32 v72, v72, v161
	v_add_f32_e32 v68, v67, v84
	v_add_f32_e32 v203, v68, v203
	v_sub_f32_e32 v68, v85, v161
	v_exp_f32_e32 v68, v68
	v_exp_f32_e32 v85, v69
	v_exp_f32_e32 v72, v72
	v_sub_f32_e32 v73, v73, v161
	v_exp_f32_e32 v73, v73
	v_add_f32_e32 v69, v68, v85
	v_add_f32_e32 v203, v69, v203
	v_sub_f32_e32 v69, v86, v161
	v_exp_f32_e32 v69, v69
	v_sub_f32_e32 v74, v74, v161
	v_exp_f32_e32 v74, v74
	v_sub_f32_e32 v75, v75, v161
	v_add_f32_e32 v86, v69, v70
	v_add_f32_e32 v203, v86, v203
	v_sub_f32_e32 v86, v87, v161
	v_exp_f32_e32 v86, v86
	v_exp_f32_e32 v75, v75
	v_sub_f32_e32 v76, v76, v161
	v_exp_f32_e32 v76, v76
	v_add_f32_e32 v87, v86, v71
	v_add_f32_e32 v203, v87, v203
	v_sub_f32_e32 v87, v88, v161
	v_exp_f32_e32 v87, v87
	v_sub_f32_e32 v77, v77, v161
	v_exp_f32_e32 v77, v77
	v_sub_f32_e32 v78, v78, v161
	v_add_f32_e32 v88, v87, v72
	v_add_f32_e32 v203, v88, v203
	v_sub_f32_e32 v88, v89, v161
	v_exp_f32_e32 v88, v88
	v_exp_f32_e32 v78, v78
	v_sub_f32_e32 v79, v79, v161
	v_exp_f32_e32 v79, v79
	v_add_f32_e32 v89, v88, v73
	v_add_f32_e32 v203, v89, v203
	v_sub_f32_e32 v89, v90, v161
	v_exp_f32_e32 v89, v89
	v_sub_f32_e32 v80, v80, v161
	v_exp_f32_e32 v80, v80
	v_sub_f32_e32 v81, v81, v161
	v_add_f32_e32 v90, v89, v74
	v_add_f32_e32 v203, v90, v203
	v_sub_f32_e32 v90, v91, v161
	v_exp_f32_e32 v90, v90
	v_exp_f32_e32 v81, v81
	v_add_f32_e32 v91, v90, v75
	v_add_f32_e32 v203, v91, v203
	v_sub_f32_e32 v91, v92, v161
	v_exp_f32_e32 v91, v91
	s_nop 0
	v_add_f32_e32 v92, v91, v76
	v_add_f32_e32 v203, v92, v203
	v_sub_f32_e32 v92, v93, v161
	v_exp_f32_e32 v92, v92
	s_nop 0
	v_add_f32_e32 v93, v92, v77
	v_add_f32_e32 v203, v93, v203
	v_sub_f32_e32 v93, v94, v161
	v_exp_f32_e32 v93, v93
	s_nop 0
	v_add_f32_e32 v94, v93, v78
	v_add_f32_e32 v203, v94, v203
	v_sub_f32_e32 v94, v95, v161
	v_exp_f32_e32 v94, v94
	s_nop 0
	v_add_f32_e32 v95, v94, v79
	v_add_f32_e32 v203, v95, v203
	v_sub_f32_e32 v95, v96, v161
	v_exp_f32_e32 v95, v95
	s_nop 0
	v_add_f32_e32 v96, v95, v80
	v_add_f32_e32 v203, v96, v203
	v_sub_f32_e32 v96, v97, v161
	v_exp_f32_e32 v96, v96
	s_nop 0
	v_add_f32_e32 v97, v96, v81
	v_add_f32_e32 v203, v97, v203
	v_cndmask_b32_e64 v97, v204, 1.0, vcc
	v_mov_b32_e32 v204, v203
	s_nop 1
	v_permlane32_swap_b32_e32 v203, v204
	v_cmp_gt_f32_e32 vcc, 1.0, v97
	s_cbranch_vccz .LBB0_850
	s_and_saveexec_b64 s[2:3], s[12:13]
	ds_write_b32 v147, v97
	s_or_b64 exec, exec, s[2:3]
	s_waitcnt lgkmcnt(0)
	ds_read_b128 v[206:209], v149 offset:96
	ds_read_b128 v[212:215], v149 offset:64
	ds_read_b128 v[216:219], v149 offset:32
	ds_read_b128 v[220:223], v149
	s_waitcnt lgkmcnt(3)
	v_pk_mul_f32 v[64:65], v[64:65], v[208:209]
	s_waitcnt lgkmcnt(2)
	v_pk_mul_f32 v[60:61], v[60:61], v[214:215]
	s_waitcnt lgkmcnt(1)
	v_pk_mul_f32 v[56:57], v[56:57], v[218:219]
	s_waitcnt lgkmcnt(0)
	v_pk_mul_f32 v[52:53], v[52:53], v[222:223]
	v_pk_mul_f32 v[62:63], v[62:63], v[206:207]
	v_pk_mul_f32 v[58:59], v[58:59], v[212:213]
	v_pk_mul_f32 v[54:55], v[54:55], v[216:217]
	v_pk_mul_f32 v[50:51], v[50:51], v[220:221]
	v_pk_mul_f32 v[48:49], v[48:49], v[208:209]
	v_pk_mul_f32 v[44:45], v[44:45], v[214:215]
	v_pk_mul_f32 v[40:41], v[40:41], v[218:219]
	v_pk_mul_f32 v[36:37], v[36:37], v[222:223]
	v_pk_mul_f32 v[46:47], v[46:47], v[206:207]
	v_pk_mul_f32 v[42:43], v[42:43], v[212:213]
	v_pk_mul_f32 v[38:39], v[38:39], v[216:217]
	v_pk_mul_f32 v[34:35], v[34:35], v[220:221]
	v_pk_mul_f32 v[32:33], v[32:33], v[208:209]
	v_pk_mul_f32 v[28:29], v[28:29], v[214:215]
	v_pk_mul_f32 v[24:25], v[24:25], v[218:219]
	v_pk_mul_f32 v[20:21], v[20:21], v[222:223]
	v_pk_mul_f32 v[30:31], v[30:31], v[206:207]
	v_pk_mul_f32 v[26:27], v[26:27], v[212:213]
	v_pk_mul_f32 v[22:23], v[22:23], v[216:217]
	v_pk_mul_f32 v[18:19], v[18:19], v[220:221]
	v_pk_mul_f32 v[16:17], v[16:17], v[208:209]
	v_pk_mul_f32 v[12:13], v[12:13], v[214:215]
	v_pk_mul_f32 v[8:9], v[8:9], v[218:219]
	v_pk_mul_f32 v[4:5], v[4:5], v[222:223]
	v_pk_mul_f32 v[14:15], v[14:15], v[206:207]
	v_pk_mul_f32 v[10:11], v[10:11], v[212:213]
	v_pk_mul_f32 v[6:7], v[6:7], v[216:217]
	v_pk_mul_f32 v[2:3], v[2:3], v[220:221]

; template <int MODE, bool SAMPLE>
; __device__ __forceinline__ void attn_unit(const Params& p, char* lds, int b, int h, int qb) {
;     ...
;         WRITET(buf, stg2[NS == 2 ? par : 0]);
;         if (j >= NS) LOADT(j - NS, stg2[NS == 2 ? par : 0]);
.LBB0_851:
	v_and_b32_e32 v76, 15, v183
	v_bfe_u32 v77, v183, 4, 3
	v_xor_b32_e32 v78, v76, v77
	v_lshrrev_b32_e32 v74, 1, v76
	v_xor_b32_e32 v74, v74, v77
	v_sub_u32_e32 v74, v74, v78
	v_and_b32_e32 v78, 1, v76
	v_lshlrev_b32_e32 v74, 4, v74
	v_lshl_add_u32 v74, v78, 3, v74
	v_lshrrev_b32_e32 v75, 3, v76
	v_lshrrev_b32_e32 v78, 2, v76
	v_sub_u32_e32 v75, v75, v78
	v_lshlrev_b32_e32 v75, 9, v75
	v_and_b32_e32 v78, 7, v76
	v_lshl_add_u32 v75, v78, 3, v75
	v_and_b32_e32 v78, 3, v76
	v_lshlrev_b32_e32 v78, 4, v78
	v_sub_u32_e32 v75, v75, v78
	v_add_u32_e32 v70, v198, v74
	v_add_u32_e32 v71, v199, v74
	v_add_u32_e32 v72, v200, v75
	v_add_u32_e32 v73, v201, v75
	s_waitcnt vmcnt(14)
	v_cvt_pk_bf16_f32 v66, v102, v103
	v_cvt_pk_bf16_f32 v67, v104, v105
	v_cvt_pk_bf16_f32 v68, v98, v99
	v_cvt_pk_bf16_f32 v69, v100, v101
	ds_write_b64 v70, v[66:67]
	ds_write_b64 v70, v[68:69] offset:128
	s_waitcnt vmcnt(12)
	v_cvt_pk_bf16_f32 v66, v110, v111
	v_cvt_pk_bf16_f32 v67, v112, v113
	v_cvt_pk_bf16_f32 v68, v106, v107
	v_cvt_pk_bf16_f32 v69, v108, v109
	ds_write_b64 v71, v[66:67]
	ds_write_b64 v71, v[68:69] offset:128
	s_waitcnt vmcnt(10)
	v_cvt_pk_bf16_f32 v66, v122, v123
	v_cvt_pk_bf16_f32 v67, v124, v125
	v_cvt_pk_bf16_f32 v68, v114, v115
	v_cvt_pk_bf16_f32 v69, v116, v117
	s_cmpk_eq_i32 s96, 0xf000
	ds_write_b64 v72, v[66:67] offset:32768
	ds_write_b64 v72, v[68:69] offset:33792
	s_waitcnt vmcnt(8)
	v_cvt_pk_bf16_f32 v66, v126, v127
	v_cvt_pk_bf16_f32 v67, v128, v129
	v_cvt_pk_bf16_f32 v68, v118, v119
	v_cvt_pk_bf16_f32 v69, v120, v121
	ds_write_b64 v73, v[66:67] offset:32768
	ds_write_b64 v73, v[68:69] offset:33792
.Lfsr_join_f2:
	s_cbranch_scc1 .LBB0_853
	s_mov_b32 s2, 0xfffe0000
	s_mov_b32 s3, -1
	v_lshl_add_u64 v[168:169], v[168:169], 0, s[2:3]
	v_or_b32_e32 v67, s61, v169
	v_or_b32_e32 v66, s9, v168
	v_readlane_b32 s36, v253, 16
	v_lshlrev_b64 v[66:67], 2, v[66:67]
	v_and_b32_e32 v72, 15, v183
	v_lshlrev_b32_e32 v72, 4, v72
	v_sub_u32_e32 v66, v66, v72
	v_readlane_b32 s40, v253, 20
	v_readlane_b32 s41, v253, 21
	v_readlane_b32 s42, v253, 22
	v_readlane_b32 s43, v253, 23
	v_lshl_add_u64 v[68:69], s[40:41], 0, v[66:67]
	v_mov_b32_e32 v163, v1
	v_lshl_add_u64 v[70:71], v[68:69], 0, v[0:1]
	v_lshl_add_u64 v[68:69], v[68:69], 0, v[162:163]
	v_lshl_add_u64 v[66:67], s[42:43], 0, v[66:67]
	global_load_dwordx4 v[98:101], v[70:71], off offset:256 nt
	global_load_dwordx4 v[102:105], v[70:71], off nt
	global_load_dwordx4 v[106:109], v[68:69], off offset:256 nt
	global_load_dwordx4 v[110:113], v[68:69], off nt
	v_lshl_add_u64 v[68:69], v[66:67], 0, v[0:1]
	v_lshl_add_u64 v[66:67], v[66:67], 0, v[162:163]
	global_load_dwordx4 v[114:117], v[68:69], off offset:256 nt
	global_load_dwordx4 v[122:125], v[68:69], off nt
	global_load_dwordx4 v[118:121], v[66:67], off offset:256 nt
	global_load_dwordx4 v[126:129], v[66:67], off nt
	v_readlane_b32 s37, v253, 17
	v_readlane_b32 s38, v253, 18
	v_readlane_b32 s39, v253, 19
	v_readlane_b32 s44, v253, 24
	v_readlane_b32 s45, v253, 25
	v_readlane_b32 s46, v253, 26
	v_readlane_b32 s47, v253, 27
	v_readlane_b32 s48, v253, 28
	v_readlane_b32 s49, v253, 29
	v_readlane_b32 s50, v253, 30
	v_readlane_b32 s51, v253, 31

; __device__ __forceinline__ unsigned cvtpk(float lo, float hi) { unsigned r; asm volatile("v_cvt_pk_bf16_f32 %0, %1, %2" : "=v"(r) : "v"(lo), "v"(hi)); return r; }
; __device__ __forceinline__ int crow(int r, int hi) { return (r & 3) + 8 * (r >> 2) + 4 * hi; }
; template <int MODE, bool SAMPLE>
; __device__ __forceinline__ void attn_unit(const Params& p, char* lds, int b, int h, int qb) {
;     ...
;     if (wact && var < 1) {
;         bf16_t* MIX = (bf16_t*)(p.ws + (var == 0 ? WS_MIX : WS_ACT));
;         const size_t rbase = SAMPLE ? (size_t)(MP + b * TS) : (size_t)(b * SEQ + qb * 256 + wid * 32);
;         constexpr int NIT = SAMPLE ? 4 : 8; const int er = lane >> 4, ec = (lane & 15) * 8;
;         float rli[16];
;         if (MODE == 0) { if (hi == 0) wsc[32 + r32] = l_reg; asm volatile("s_waitcnt lgkmcnt(0)" ::: "memory");
; #pragma unroll
;             for (int r = 0; r < 16; ++r) rli[r] = __builtin_amdgcn_rcpf(wsc[32 + crow(r, hi)]); }
; #pragma unroll
;         for (int r = 0; r < 16; ++r) { const int orow = crow(r, hi);
;             if (!SAMPLE || orow < TS) {
; #pragma unroll
;                 for (int d0 = 0; d0 < 4; ++d0) { float ov = o[d0][r]; if (MODE == 0) ov *= rli[r];
;                     const unsigned pk = cvtpk(ov, 0.f); *(bf16_t*)(Qs + orow * 256 + (d0 * 32 + r32) * 2) = (bf16_t)(pk & 0xffffu); } } }
.LBB0_859:
	s_waitcnt vmcnt(0)
	v_mov_b32_e32 v141, v250
	v_mov_b32_e32 v143, v251
	v_mov_b32_e32 v130, v252
	v_and_b32_e32 v131, 31, v183
	v_bfe_u32 v132, v183, 4, 2
	v_lshlrev_b32_e32 v133, 8, v131
	v_or_b32_e32 v140, 8, v132
	v_or_b32_e32 v142, 12, v132
	v_lshlrev_b32_e32 v192, 1, v131
	v_lshlrev_b32_e32 v193, 8, v132
	v_lshlrev_b32_e32 v194, 8, v138
	v_lshlrev_b32_e32 v195, 8, v140
	s_andn2_b64 vcc, exec, s[72:73]
	s_mov_b64 s[0:1], -1
	s_cbranch_vccnz .LBB0_861
	s_mov_b32 s61, s53
	s_mov_b64 s[0:1], 0
